# v12 + unit scheduler: the two 64-bit VALU compares (L vs nwg) replaced by s_cmp_lt_u32 + s_cselect_b64 in all 12 GEMM phases
# baseline (speedup 1.0000x reference)
;     __device__ __forceinline__ bool next(int i, Unit& u) const {
;     ...
;         const long L = (long)i * G + c; if (L >= nwg) return false;
;         int wgid = (int)L; { const int q = nwg / NXCD, r = nwg % NXCD, xcd = wgid % NXCD, off = wgid / NXCD; wgid = (xcd < r ? xcd * (q + 1) : r * (q + 1) + (xcd - r) * q) + off; }
;         if (rev) wgid = nwg - 1 - wgid;
;         const int per = nM * nN, z = wgid / per, rem = wgid - z * per;
;         const int nig = WGM * nN, gid = rem / nig, fm = gid * WGM, gsz = (nM - fm) < WGM ? (nM - fm) : WGM, ri = rem - gid * nig;
;         u.pm = fm + (ri % gsz); u.pn = ri / gsz; u.z1 = z / Z2; u.z2 = z - u.z1 * Z2; return true;
.LBB0_217:
	s_mov_b32 s8, 20
	s_mov_b32 s10, 1
	s_mov_b32 s9, 16
	s_add_i32 s89, s89, 1
	s_mul_i32 s10, s89, s88
	s_mul_hi_u32 s11, s89, s0
	s_add_i32 s11, s11, s10
	s_mul_i32 s10, s89, s0
	s_add_u32 s10, s10, s1
	s_addc_u32 s11, s11, s67
	s_cmp_lt_u32 s10, 0x140
	s_cselect_b64 s[40:41], exec, 0
	s_cselect_b64 vcc, 0, exec
	s_cbranch_vccnz .LBB0_219
	s_ashr_i32 s11, s10, 31
	s_lshr_b32 s11, s11, 29
	s_add_i32 s11, s10, s11
	s_ashr_i32 s12, s11, 3
	s_and_b32 s11, s11, -8
	s_sub_i32 s10, s10, s11
	s_cmp_lt_i32 s10, 0
	s_mul_i32 s13, s8, s9
	s_cselect_b32 s11, 41, 40
	s_abs_i32 s13, s13
	s_mul_i32 s10, s10, s11
	s_sub_i32 s11, 0, s13
	s_add_i32 s10, s10, s12
	s_ashr_i32 s12, s10, 31
	s_abs_i32 s10, s10
	s_mov_b32 s20, 0xcccccc
	s_mul_hi_u32 s11, s10, s20
	s_mul_i32 s11, s11, s13
	s_sub_i32 s10, s10, s11
	s_sub_i32 s11, s10, s13
	s_cmp_ge_u32 s10, s13
	s_cselect_b32 s10, s11, s10
	s_sub_i32 s11, s10, s13
	s_cmp_ge_u32 s10, s13
	s_cselect_b32 s10, s11, s10
	s_lshl_b32 s9, s9, 2
	s_abs_i32 s11, s9
	s_xor_b32 s10, s10, s12
	s_sub_i32 s10, s10, s12
	s_sub_i32 s12, 0, s11
	s_abs_i32 s20, s10
	s_xor_b32 s13, s10, s9
	s_ashr_i32 s13, s13, 31
	s_mov_b32 s21, 0x4000000
	s_mul_hi_u32 s12, s20, s21
	s_mul_i32 s21, s12, s11
	s_sub_i32 s20, s20, s21
	s_add_i32 s30, s12, 1
	s_sub_i32 s21, s20, s11
	s_cmp_ge_u32 s20, s11
	s_cselect_b32 s12, s30, s12
	s_cselect_b32 s20, s21, s20
	s_add_i32 s21, s12, 1
	s_cmp_ge_u32 s20, s11
	s_cselect_b32 s11, s21, s12
	s_xor_b32 s11, s11, s13
	s_sub_i32 s11, s11, s13
	s_lshl_b32 s13, s11, 2
	s_sub_i32 s8, s8, s13
	s_min_i32 s8, s8, 4
	s_abs_i32 s12, s8
	s_sub_i32 s20, 0, s12
	s_mul_i32 s11, s11, s9
	s_sub_i32 s9, s10, s11
	s_abs_i32 s10, s9
	s_xor_b32 s11, s9, s8
	s_ashr_i32 s11, s11, 31
	s_mov_b32 s21, 0x40000000
	s_mul_hi_u32 s20, s10, s21
	s_mul_i32 s21, s20, s12
	s_sub_i32 s10, s10, s21
	s_add_i32 s30, s20, 1
	s_sub_i32 s21, s10, s12
	s_cmp_ge_u32 s10, s12
	s_cselect_b32 s20, s30, s20
	s_cselect_b32 s10, s21, s10
	s_add_i32 s21, s20, 1
	s_cmp_ge_u32 s10, s12
	s_cselect_b32 s10, s21, s20
	s_xor_b32 s10, s10, s11
	s_sub_i32 s12, s10, s11
	s_mul_i32 s8, s12, s8
	s_sub_i32 s8, s9, s8
	s_add_i32 s20, s13, s8

;     __device__ __forceinline__ bool next(int i, Unit& u) const {
;     ...
;         const long L = (long)i * G + c; if (L >= nwg) return false;
;         int wgid = (int)L; { const int q = nwg / NXCD, r = nwg % NXCD, xcd = wgid % NXCD, off = wgid / NXCD; wgid = (xcd < r ? xcd * (q + 1) : r * (q + 1) + (xcd - r) * q) + off; }
;         if (rev) wgid = nwg - 1 - wgid;
;         const int per = nM * nN, z = wgid / per, rem = wgid - z * per;
;         const int nig = WGM * nN, gid = rem / nig, fm = gid * WGM, gsz = (nM - fm) < WGM ? (nM - fm) : WGM, ri = rem - gid * nig;
;         u.pm = fm + (ri % gsz); u.pn = ri / gsz; u.z1 = z / Z2; u.z2 = z - u.z1 * Z2; return true;
.LBB0_235:
	s_mov_b32 s10, 1
	s_movk_i32 s8, 0xa0
	s_mov_b32 s9, 28
	s_add_i32 s96, s96, 1
	s_mul_i32 s10, s96, s95
	s_mul_hi_u32 s11, s96, s0
	s_add_i32 s11, s11, s10
	s_mul_i32 s10, s96, s0
	s_add_u32 s10, s10, s2
	s_addc_u32 s11, s11, s33
	s_cmp_lt_u32 s10, 0x1180
	s_cselect_b64 s[40:41], exec, 0
	s_cselect_b64 s[42:43], 0, exec
	s_and_b64 vcc, exec, s[42:43]
	s_cbranch_vccnz .LBB0_237
	s_ashr_i32 s11, s10, 31
	s_lshr_b32 s11, s11, 29
	s_add_i32 s11, s10, s11
	s_and_b32 s13, s11, -8
	s_sub_i32 s10, s10, s13
	s_ashr_i32 s11, s11, 3
	s_cmp_lt_i32 s10, 0
	s_mul_i32 s36, s8, s9
	s_cselect_b32 s13, s4, 0xfffffdd0
	s_abs_i32 s36, s36
	s_mul_i32 s10, s10, s13
	s_sub_i32 s13, 0, s36
	s_sub_i32 s10, s10, s11
	s_addk_i32 s10, 0x117f
	s_ashr_i32 s11, s10, 31
	s_abs_i32 s10, s10
	s_mov_b32 s37, 0xea0ea
	s_mul_hi_u32 s13, s10, s37
	s_mul_i32 s13, s13, s36
	s_sub_i32 s10, s10, s13
	s_sub_i32 s13, s10, s36
	s_cmp_ge_u32 s10, s36
	s_cselect_b32 s10, s13, s10
	s_sub_i32 s13, s10, s36
	s_cmp_ge_u32 s10, s36
	s_cselect_b32 s10, s13, s10
	s_lshl_b32 s9, s9, 2
	s_abs_i32 s13, s9
	s_xor_b32 s10, s10, s11
	s_sub_i32 s10, s10, s11
	s_sub_i32 s11, 0, s13
	s_abs_i32 s37, s10
	s_xor_b32 s36, s10, s9
	s_ashr_i32 s36, s36, 31
	s_mov_b32 s44, 0x2492492
	s_mul_hi_u32 s11, s37, s44
	s_mul_i32 s44, s11, s13
	s_sub_i32 s37, s37, s44
	s_add_i32 s45, s11, 1
	s_sub_i32 s44, s37, s13
	s_cmp_ge_u32 s37, s13
	s_cselect_b32 s11, s45, s11
	s_cselect_b32 s37, s44, s37
	s_add_i32 s44, s11, 1
	s_cmp_ge_u32 s37, s13
	s_cselect_b32 s11, s44, s11
	s_xor_b32 s11, s11, s36
	s_sub_i32 s11, s11, s36
	s_lshl_b32 s13, s11, 2
	s_sub_i32 s8, s8, s13
	s_min_i32 s8, s8, 4
	s_abs_i32 s36, s8
	s_sub_i32 s37, 0, s36
	s_mul_i32 s11, s11, s9
	s_sub_i32 s9, s10, s11
	s_abs_i32 s10, s9
	s_xor_b32 s11, s9, s8
	s_ashr_i32 s11, s11, 31
	s_mov_b32 s44, 0x40000000
	s_mul_hi_u32 s37, s10, s44
	s_mul_i32 s44, s37, s36
	s_sub_i32 s10, s10, s44
	s_add_i32 s45, s37, 1
	s_sub_i32 s44, s10, s36
	s_cmp_ge_u32 s10, s36
	s_cselect_b32 s37, s45, s37
	s_cselect_b32 s10, s44, s10
	s_add_i32 s44, s37, 1
	s_cmp_ge_u32 s10, s36
	s_cselect_b32 s10, s44, s37
	s_xor_b32 s10, s10, s11
	s_sub_i32 s56, s10, s11
	s_mul_i32 s8, s56, s8
	s_sub_i32 s8, s9, s8
	s_add_i32 s58, s13, s8

;     __device__ __forceinline__ bool next(int i, Unit& u) const {
;     ...
;         const long L = (long)i * G + c; if (L >= nwg) return false;
;         int wgid = (int)L; { const int q = nwg / NXCD, r = nwg % NXCD, xcd = wgid % NXCD, off = wgid / NXCD; wgid = (xcd < r ? xcd * (q + 1) : r * (q + 1) + (xcd - r) * q) + off; }
;         if (rev) wgid = nwg - 1 - wgid;
;         const int per = nM * nN, z = wgid / per, rem = wgid - z * per;
;         const int nig = WGM * nN, gid = rem / nig, fm = gid * WGM, gsz = (nM - fm) < WGM ? (nM - fm) : WGM, ri = rem - gid * nig;
;         u.pm = fm + (ri % gsz); u.pn = ri / gsz; u.z1 = z / Z2; u.z2 = z - u.z1 * Z2; return true;
.LBB0_401:
	s_add_i32 s91, s91, 1
	s_mul_i32 s10, s91, s90
	s_mul_hi_u32 s11, s91, s87
	s_add_i32 s11, s11, s10
	s_mul_i32 s10, s91, s87
	s_add_u32 s10, s10, s2
	s_addc_u32 s11, s11, s33
	s_mov_b32 s21, 8
	s_mov_b32 s9, 1
	s_mov_b32 s8, 4
	s_cmp_lt_u32 s10, 0x280
	s_cselect_b64 s[46:47], exec, 0
	s_cselect_b64 vcc, 0, exec
	s_cbranch_vccnz .LBB0_403
	s_ashr_i32 s11, s10, 31
	s_lshr_b32 s11, s11, 29
	s_add_i32 s11, s10, s11
	s_ashr_i32 s20, s11, 3
	s_and_b32 s11, s11, -8
	s_sub_i32 s10, s10, s11
	s_cmp_lt_i32 s10, 0
	s_movk_i32 s4, 0x51
	s_mul_i32 s30, s9, s21
	s_cselect_b32 s11, s4, 0x50
	s_abs_i32 s31, s30
	s_mul_i32 s10, s10, s11
	s_sub_i32 s11, 0, s31
	s_add_i32 s10, s10, s20
	s_abs_i32 s37, s10
	s_xor_b32 s20, s10, s30
	s_ashr_i32 s20, s20, 31
	s_mov_b32 s40, 0x20000000
	s_mul_hi_u32 s11, s37, s40
	s_mul_i32 s40, s11, s31
	s_sub_i32 s37, s37, s40
	s_add_i32 s40, s11, 1
	s_sub_i32 s41, s37, s31
	s_cmp_ge_u32 s37, s31
	s_cselect_b32 s11, s40, s11
	s_cselect_b32 s37, s41, s37
	s_add_i32 s40, s11, 1
	s_cmp_ge_u32 s37, s31
	s_cselect_b32 s11, s40, s11
	s_lshl_b32 s21, s21, 2
	s_abs_i32 s31, s21
	s_xor_b32 s11, s11, s20
	s_sub_i32 s11, s11, s20
	s_sub_i32 s37, 0, s31
	s_mul_i32 s20, s11, s30
	s_sub_i32 s10, s10, s20
	s_abs_i32 s30, s10
	s_xor_b32 s20, s10, s21
	s_ashr_i32 s20, s20, 31
	s_mov_b32 s40, 0x8000000
	s_mul_hi_u32 s37, s30, s40
	s_mul_i32 s40, s37, s31
	s_sub_i32 s30, s30, s40
	s_add_i32 s40, s37, 1
	s_sub_i32 s41, s30, s31
	s_cmp_ge_u32 s30, s31
	s_cselect_b32 s37, s40, s37
	s_cselect_b32 s30, s41, s30
	s_add_i32 s40, s37, 1
	s_cmp_ge_u32 s30, s31
	s_cselect_b32 s30, s40, s37
	s_xor_b32 s30, s30, s20
	s_sub_i32 s20, s30, s20
	s_lshl_b32 s30, s20, 2
	s_sub_i32 s9, s9, s30
	s_min_i32 s9, s9, 4
	s_abs_i32 s31, s9
	v_cvt_f32_u32_e32 v0, s31
	s_sub_i32 s37, 0, s31
	s_mul_i32 s20, s20, s21
	s_sub_i32 s10, s10, s20
	v_rcp_iflag_f32_e32 v0, v0
	s_abs_i32 s21, s10
	s_xor_b32 s20, s10, s9
	s_ashr_i32 s20, s20, 31
	v_mul_f32_e32 v0, 0x4f7ffffe, v0
	v_cvt_u32_f32_e32 v0, v0
	s_nop 0
	v_readfirstlane_b32 s40, v0
	s_mul_i32 s37, s37, s40
	s_mul_hi_u32 s37, s40, s37
	s_add_i32 s40, s40, s37
	s_mul_hi_u32 s37, s21, s40
	s_mul_i32 s40, s37, s31
	s_sub_i32 s21, s21, s40
	s_add_i32 s40, s37, 1
	s_sub_i32 s41, s21, s31
	s_cmp_ge_u32 s21, s31
	s_cselect_b32 s37, s40, s37
	s_cselect_b32 s21, s41, s21
	s_add_i32 s40, s37, 1
	s_cmp_ge_u32 s21, s31
	s_cselect_b32 s21, s40, s37
	s_abs_i32 s31, s8
	s_xor_b32 s21, s21, s20
	s_sub_i32 s20, s21, s20
	s_sub_i32 s21, 0, s31
	s_mul_i32 s9, s20, s9
	s_sub_i32 s9, s10, s9
	s_abs_i32 s10, s11
	s_add_i32 s30, s30, s9
	s_xor_b32 s9, s11, s8
	s_ashr_i32 s9, s9, 31
	s_mov_b32 s37, 0x40000000
	s_mul_hi_u32 s21, s10, s37
	s_mul_i32 s37, s21, s31
	s_sub_i32 s10, s10, s37
	s_add_i32 s37, s21, 1
	s_sub_i32 s40, s10, s31
	s_cmp_ge_u32 s10, s31
	s_cselect_b32 s21, s37, s21
	s_cselect_b32 s10, s40, s10
	s_add_i32 s37, s21, 1
	s_cmp_ge_u32 s10, s31
	s_cselect_b32 s10, s37, s21
	s_xor_b32 s10, s10, s9
	s_sub_i32 s44, s10, s9
	s_mul_i32 s8, s44, s8
	s_sub_i32 s48, s11, s8

;     __device__ __forceinline__ bool next(int i, Unit& u) const {
;     ...
;         const long L = (long)i * G + c; if (L >= nwg) return false;
;         int wgid = (int)L; { const int q = nwg / NXCD, r = nwg % NXCD, xcd = wgid % NXCD, off = wgid / NXCD; wgid = (xcd < r ? xcd * (q + 1) : r * (q + 1) + (xcd - r) * q) + off; }
;         if (rev) wgid = nwg - 1 - wgid;
;         const int per = nM * nN, z = wgid / per, rem = wgid - z * per;
;         const int nig = WGM * nN, gid = rem / nig, fm = gid * WGM, gsz = (nM - fm) < WGM ? (nM - fm) : WGM, ri = rem - gid * nig;
;         u.pm = fm + (ri % gsz); u.pn = ri / gsz; u.z1 = z / Z2; u.z2 = z - u.z1 * Z2; return true;
.LBB0_421:
	s_add_i32 s93, s93, 1
	s_mul_i32 s10, s93, s92
	s_mul_hi_u32 s11, s93, s87
	s_add_i32 s11, s11, s10
	s_mul_i32 s10, s93, s87
	s_add_u32 s10, s10, s0
	s_addc_u32 s11, s11, s68
	s_mov_b32 s9, 8
	s_mov_b32 s21, 1
	s_mov_b32 s8, 4
	s_cmp_lt_u32 s10, 0x280
	s_cselect_b64 s[46:47], exec, 0
	s_cselect_b64 vcc, 0, exec
	s_cbranch_vccnz .LBB0_423
	s_ashr_i32 s11, s10, 31
	s_lshr_b32 s11, s11, 29
	s_add_i32 s11, s10, s11
	s_ashr_i32 s30, s11, 3
	s_and_b32 s11, s11, -8
	s_sub_i32 s10, s10, s11
	s_cmp_lt_i32 s10, 0
	s_movk_i32 s4, 0x51
	s_mul_i32 s31, s9, s21
	s_cselect_b32 s11, s4, 0x50
	s_abs_i32 s36, s31
	s_mul_i32 s10, s10, s11
	s_sub_i32 s11, 0, s36
	s_add_i32 s10, s10, s30
	s_abs_i32 s37, s10
	s_xor_b32 s30, s10, s31
	s_ashr_i32 s30, s30, 31
	s_mov_b32 s40, 0x20000000
	s_mul_hi_u32 s11, s37, s40
	s_mul_i32 s40, s11, s36
	s_sub_i32 s37, s37, s40
	s_add_i32 s40, s11, 1
	s_sub_i32 s41, s37, s36
	s_cmp_ge_u32 s37, s36
	s_cselect_b32 s11, s40, s11
	s_cselect_b32 s37, s41, s37
	s_add_i32 s40, s11, 1
	s_cmp_ge_u32 s37, s36
	s_cselect_b32 s11, s40, s11
	s_lshl_b32 s21, s21, 2
	s_abs_i32 s36, s21
	s_xor_b32 s11, s11, s30
	s_sub_i32 s11, s11, s30
	s_sub_i32 s37, 0, s36
	s_mul_i32 s30, s11, s31
	s_sub_i32 s10, s10, s30
	s_abs_i32 s31, s10
	s_xor_b32 s30, s10, s21
	s_ashr_i32 s30, s30, 31
	s_mov_b32 s40, 0x40000000
	s_mul_hi_u32 s37, s31, s40
	s_mul_i32 s40, s37, s36
	s_sub_i32 s31, s31, s40
	s_add_i32 s40, s37, 1
	s_sub_i32 s41, s31, s36
	s_cmp_ge_u32 s31, s36
	s_cselect_b32 s37, s40, s37
	s_cselect_b32 s31, s41, s31
	s_add_i32 s40, s37, 1
	s_cmp_ge_u32 s31, s36
	s_cselect_b32 s31, s40, s37
	s_xor_b32 s31, s31, s30
	s_sub_i32 s30, s31, s30
	s_lshl_b32 s31, s30, 2
	s_sub_i32 s9, s9, s31
	s_min_i32 s9, s9, 4
	s_abs_i32 s36, s9
	s_sub_i32 s37, 0, s36
	s_mul_i32 s30, s30, s21
	s_sub_i32 s10, s10, s30
	s_abs_i32 s30, s10
	s_xor_b32 s21, s10, s9
	s_ashr_i32 s21, s21, 31
	s_mov_b32 s40, 0x40000000
	s_mul_hi_u32 s37, s30, s40
	s_mul_i32 s40, s37, s36
	s_sub_i32 s30, s30, s40
	s_add_i32 s40, s37, 1
	s_sub_i32 s41, s30, s36
	s_cmp_ge_u32 s30, s36
	s_cselect_b32 s37, s40, s37
	s_cselect_b32 s30, s41, s30
	s_add_i32 s40, s37, 1
	s_cmp_ge_u32 s30, s36
	s_cselect_b32 s30, s40, s37
	s_abs_i32 s37, s8
	s_xor_b32 s30, s30, s21
	s_sub_i32 s30, s30, s21
	s_mul_i32 s9, s30, s9
	s_sub_i32 s9, s10, s9
	s_add_i32 s36, s31, s9
	s_sub_i32 s21, 0, s37
	s_abs_i32 s10, s11
	s_xor_b32 s9, s11, s8
	s_ashr_i32 s9, s9, 31
	s_mov_b32 s31, 0x40000000
	s_mul_hi_u32 s21, s10, s31
	s_mul_i32 s31, s21, s37
	s_sub_i32 s10, s10, s31
	s_add_i32 s31, s21, 1
	s_sub_i32 s40, s10, s37
	s_cmp_ge_u32 s10, s37
	s_cselect_b32 s21, s31, s21
	s_cselect_b32 s10, s40, s10
	s_add_i32 s31, s21, 1
	s_cmp_ge_u32 s10, s37
	s_cselect_b32 s10, s31, s21
	s_xor_b32 s10, s10, s9
	s_sub_i32 s50, s10, s9
	s_mul_i32 s8, s50, s8
	s_sub_i32 s52, s11, s8

;     __device__ __forceinline__ bool next(int i, Unit& u) const {
;     ...
;         const long L = (long)i * G + c; if (L >= nwg) return false;
;         int wgid = (int)L; { const int q = nwg / NXCD, r = nwg % NXCD, xcd = wgid % NXCD, off = wgid / NXCD; wgid = (xcd < r ? xcd * (q + 1) : r * (q + 1) + (xcd - r) * q) + off; }
;         if (rev) wgid = nwg - 1 - wgid;
;         const int per = nM * nN, z = wgid / per, rem = wgid - z * per;
;         const int nig = WGM * nN, gid = rem / nig, fm = gid * WGM, gsz = (nM - fm) < WGM ? (nM - fm) : WGM, ri = rem - gid * nig;
;         u.pm = fm + (ri % gsz); u.pn = ri / gsz; u.z1 = z / Z2; u.z2 = z - u.z1 * Z2; return true;
.LBB0_504:
	s_mov_b32 s10, 8
	s_mov_b32 s11, 1
	s_mov_b32 s12, 1
	s_cmp_lt_u32 s20, 0x500
	s_cselect_b64 s[48:49], exec, 0
	s_cselect_b64 vcc, 0, exec
	s_cbranch_vccnz .LBB0_506
	s_ashr_i32 s13, s20, 31
	s_lshr_b32 s13, s13, 29
	s_add_i32 s13, s20, s13
	s_ashr_i32 s30, s13, 3
	s_and_b32 s13, s13, -8
	s_sub_i32 s13, s20, s13
	s_cmp_lt_i32 s13, 0
	s_movk_i32 s4, 0xa1
	s_mul_i32 s36, s11, s12
	s_cselect_b32 s31, s4, 0xa0
	s_abs_i32 s37, s36
	s_mul_i32 s13, s13, s31
	s_sub_i32 s31, 0, s37
	s_add_i32 s13, s13, s30
	s_abs_i32 s40, s13
	s_xor_b32 s30, s13, s36
	s_ashr_i32 s30, s30, 31
	s_mov_b32 s41, 0xffffffff
	s_mul_hi_u32 s31, s40, s41
	s_mul_i32 s41, s31, s37
	s_sub_i32 s40, s40, s41
	s_add_i32 s41, s31, 1
	s_sub_i32 s42, s40, s37
	s_cmp_ge_u32 s40, s37
	s_cselect_b32 s31, s41, s31
	s_cselect_b32 s40, s42, s40
	s_add_i32 s41, s31, 1
	s_cmp_ge_u32 s40, s37
	s_cselect_b32 s31, s41, s31
	s_lshl_b32 s12, s12, 2
	s_abs_i32 s37, s12
	s_xor_b32 s31, s31, s30
	s_sub_i32 s31, s31, s30
	s_sub_i32 s40, 0, s37
	s_mul_i32 s30, s31, s36
	s_sub_i32 s13, s13, s30
	s_abs_i32 s36, s13
	s_xor_b32 s30, s13, s12
	s_ashr_i32 s30, s30, 31
	s_mov_b32 s41, 0x40000000
	s_mul_hi_u32 s40, s36, s41
	s_mul_i32 s41, s40, s37
	s_sub_i32 s36, s36, s41
	s_add_i32 s41, s40, 1
	s_sub_i32 s42, s36, s37
	s_cmp_ge_u32 s36, s37
	s_cselect_b32 s40, s41, s40
	s_cselect_b32 s36, s42, s36
	s_add_i32 s41, s40, 1
	s_cmp_ge_u32 s36, s37
	s_cselect_b32 s36, s41, s40
	s_xor_b32 s36, s36, s30
	s_sub_i32 s30, s36, s30
	s_lshl_b32 s36, s30, 2
	s_sub_i32 s11, s11, s36
	s_min_i32 s11, s11, 4
	s_abs_i32 s37, s11
	v_cvt_f32_u32_e32 v0, s37
	s_sub_i32 s40, 0, s37
	s_mul_i32 s30, s30, s12
	s_sub_i32 s12, s13, s30
	v_rcp_iflag_f32_e32 v0, v0
	s_abs_i32 s30, s12
	s_xor_b32 s13, s12, s11
	s_ashr_i32 s13, s13, 31
	v_mul_f32_e32 v0, 0x4f7ffffe, v0
	v_cvt_u32_f32_e32 v0, v0
	s_nop 0
	v_readfirstlane_b32 s41, v0
	s_mul_i32 s40, s40, s41
	s_mul_hi_u32 s40, s41, s40
	s_add_i32 s41, s41, s40
	s_mul_hi_u32 s40, s30, s41
	s_mul_i32 s41, s40, s37
	s_sub_i32 s30, s30, s41
	s_add_i32 s41, s40, 1
	s_sub_i32 s42, s30, s37
	s_cmp_ge_u32 s30, s37
	s_cselect_b32 s40, s41, s40
	s_cselect_b32 s30, s42, s30
	s_add_i32 s41, s40, 1
	s_cmp_ge_u32 s30, s37
	s_cselect_b32 s30, s41, s40
	s_abs_i32 s37, s10
	s_xor_b32 s30, s30, s13
	s_sub_i32 s30, s30, s13
	s_sub_i32 s13, 0, s37
	s_mul_i32 s11, s30, s11
	s_sub_i32 s11, s12, s11
	s_abs_i32 s12, s31
	s_add_i32 s36, s36, s11
	s_xor_b32 s11, s31, s10
	s_ashr_i32 s11, s11, 31
	s_mov_b32 s40, 0x20000000
	s_mul_hi_u32 s13, s12, s40
	s_mul_i32 s40, s13, s37
	s_sub_i32 s12, s12, s40
	s_add_i32 s40, s13, 1
	s_sub_i32 s41, s12, s37
	s_cmp_ge_u32 s12, s37
	s_cselect_b32 s13, s40, s13
	s_cselect_b32 s12, s41, s12
	s_add_i32 s40, s13, 1
	s_cmp_ge_u32 s12, s37
	s_cselect_b32 s12, s40, s13
	s_xor_b32 s12, s12, s11
	s_sub_i32 s40, s12, s11
	s_mul_i32 s10, s40, s10
	s_sub_i32 s42, s31, s10

;     __device__ __forceinline__ bool next(int i, Unit& u) const {
;     ...
;         const long L = (long)i * G + c; if (L >= nwg) return false;
;         int wgid = (int)L; { const int q = nwg / NXCD, r = nwg % NXCD, xcd = wgid % NXCD, off = wgid / NXCD; wgid = (xcd < r ? xcd * (q + 1) : r * (q + 1) + (xcd - r) * q) + off; }
;         if (rev) wgid = nwg - 1 - wgid;
;         const int per = nM * nN, z = wgid / per, rem = wgid - z * per;
;         const int nig = WGM * nN, gid = rem / nig, fm = gid * WGM, gsz = (nM - fm) < WGM ? (nM - fm) : WGM, ri = rem - gid * nig;
;         u.pm = fm + (ri % gsz); u.pn = ri / gsz; u.z1 = z / Z2; u.z2 = z - u.z1 * Z2; return true;
.LBB0_524:
	s_mov_b32 s10, 1
	s_movk_i32 s8, 0xa0
	s_mov_b32 s9, 16
	s_add_i32 s95, s95, 1
	s_mul_i32 s10, s95, s94
	s_mul_hi_u32 s11, s95, s87
	s_add_i32 s11, s11, s10
	s_mul_i32 s10, s95, s87
	s_add_u32 s10, s10, s2
	s_addc_u32 s11, s11, s33
	s_cmp_lt_u32 s10, 0xa00
	s_cselect_b64 s[46:47], exec, 0
	s_cselect_b64 s[48:49], 0, exec
	s_and_b64 vcc, exec, s[48:49]
	s_cbranch_vccnz .LBB0_526
	s_ashr_i32 s11, s10, 31
	s_lshr_b32 s11, s11, 29
	s_add_i32 s11, s10, s11
	s_ashr_i32 s30, s11, 3
	s_and_b32 s11, s11, -8
	s_sub_i32 s10, s10, s11
	s_cmp_lt_i32 s10, 0
	s_mul_i32 s31, s8, s9
	s_cselect_b32 s11, s4, 0x140
	s_abs_i32 s31, s31
	s_mul_i32 s10, s10, s11
	s_sub_i32 s11, 0, s31
	s_add_i32 s10, s10, s30
	s_ashr_i32 s30, s10, 31
	s_abs_i32 s10, s10
	s_mov_b32 s36, 0x199999
	s_mul_hi_u32 s11, s10, s36
	s_mul_i32 s11, s11, s31
	s_sub_i32 s10, s10, s11
	s_sub_i32 s11, s10, s31
	s_cmp_ge_u32 s10, s31
	s_cselect_b32 s10, s11, s10
	s_sub_i32 s11, s10, s31
	s_cmp_ge_u32 s10, s31
	s_cselect_b32 s10, s11, s10
	s_lshl_b32 s9, s9, 2
	s_abs_i32 s11, s9
	s_xor_b32 s10, s10, s30
	s_sub_i32 s10, s10, s30
	s_sub_i32 s30, 0, s11
	s_abs_i32 s36, s10
	s_xor_b32 s31, s10, s9
	s_ashr_i32 s31, s31, 31
	s_mov_b32 s37, 0x4000000
	s_mul_hi_u32 s30, s36, s37
	s_mul_i32 s37, s30, s11
	s_sub_i32 s36, s36, s37
	s_add_i32 s42, s30, 1
	s_sub_i32 s37, s36, s11
	s_cmp_ge_u32 s36, s11
	s_cselect_b32 s30, s42, s30
	s_cselect_b32 s36, s37, s36
	s_add_i32 s37, s30, 1
	s_cmp_ge_u32 s36, s11
	s_cselect_b32 s11, s37, s30
	s_xor_b32 s11, s11, s31
	s_sub_i32 s11, s11, s31
	s_lshl_b32 s30, s11, 2
	s_sub_i32 s8, s8, s30
	s_min_i32 s8, s8, 4
	s_abs_i32 s31, s8
	s_sub_i32 s36, 0, s31
	s_mul_i32 s11, s11, s9
	s_sub_i32 s9, s10, s11
	s_abs_i32 s10, s9
	s_xor_b32 s11, s9, s8
	s_ashr_i32 s11, s11, 31
	s_mov_b32 s37, 0x40000000
	s_mul_hi_u32 s36, s10, s37
	s_mul_i32 s37, s36, s31
	s_sub_i32 s10, s10, s37
	s_add_i32 s42, s36, 1
	s_sub_i32 s37, s10, s31
	s_cmp_ge_u32 s10, s31
	s_cselect_b32 s36, s42, s36
	s_cselect_b32 s10, s37, s10
	s_add_i32 s37, s36, 1
	s_cmp_ge_u32 s10, s31
	s_cselect_b32 s10, s37, s36
	s_xor_b32 s10, s10, s11
	s_sub_i32 s58, s10, s11
	s_mul_i32 s8, s58, s8
	s_sub_i32 s8, s9, s8
	s_add_i32 s36, s30, s8

;     __device__ __forceinline__ bool next(int i, Unit& u) const {
;     ...
;         const long L = (long)i * G + c; if (L >= nwg) return false;
;         int wgid = (int)L; { const int q = nwg / NXCD, r = nwg % NXCD, xcd = wgid % NXCD, off = wgid / NXCD; wgid = (xcd < r ? xcd * (q + 1) : r * (q + 1) + (xcd - r) * q) + off; }
;         if (rev) wgid = nwg - 1 - wgid;
;         const int per = nM * nN, z = wgid / per, rem = wgid - z * per;
;         const int nig = WGM * nN, gid = rem / nig, fm = gid * WGM, gsz = (nM - fm) < WGM ? (nM - fm) : WGM, ri = rem - gid * nig;
;         u.pm = fm + (ri % gsz); u.pn = ri / gsz; u.z1 = z / Z2; u.z2 = z - u.z1 * Z2; return true;
.LBB0_684:
	s_mov_b32 s20, 8
	s_mov_b32 s10, 1
	s_movk_i32 s13, 0xa0
	s_add_i32 s88, s88, 1
	s_mul_i32 s10, s88, s87
	s_mul_hi_u32 s11, s88, s0
	s_add_i32 s11, s11, s10
	s_mul_i32 s10, s88, s0
	s_add_u32 s10, s10, s2
	s_addc_u32 s11, s11, s33
	s_cmp_lt_u32 s10, 0x500
	s_cselect_b64 s[48:49], exec, 0
	s_cselect_b64 vcc, 0, exec
	s_cbranch_vccnz .LBB0_686
	s_ashr_i32 s11, s10, 31
	s_lshr_b32 s11, s11, 29
	s_add_i32 s11, s10, s11
	s_and_b32 s12, s11, -8
	s_sub_i32 s10, s10, s12
	s_ashr_i32 s11, s11, 3
	s_cmp_lt_i32 s10, 0
	s_mul_i32 s21, s13, s20
	s_cselect_b32 s12, s4, 0xffffff60
	s_abs_i32 s21, s21
	s_mul_i32 s10, s10, s12
	s_sub_i32 s12, 0, s21
	s_sub_i32 s10, s10, s11
	s_addk_i32 s10, 0x4ff
	s_ashr_i32 s11, s10, 31
	s_abs_i32 s10, s10
	s_mov_b32 s30, 0x333333
	s_mul_hi_u32 s12, s10, s30
	s_mul_i32 s12, s12, s21
	s_sub_i32 s10, s10, s12
	s_sub_i32 s12, s10, s21
	s_cmp_ge_u32 s10, s21
	s_cselect_b32 s10, s12, s10
	s_sub_i32 s12, s10, s21
	s_cmp_ge_u32 s10, s21
	s_cselect_b32 s10, s12, s10
	s_lshl_b32 s12, s20, 2
	s_abs_i32 s20, s12
	s_xor_b32 s10, s10, s11
	s_sub_i32 s10, s10, s11
	s_sub_i32 s11, 0, s20
	s_abs_i32 s30, s10
	s_xor_b32 s21, s10, s12
	s_ashr_i32 s21, s21, 31
	s_mov_b32 s31, 0x8000000
	s_mul_hi_u32 s11, s30, s31
	s_mul_i32 s31, s11, s20
	s_sub_i32 s30, s30, s31
	s_add_i32 s41, s11, 1
	s_sub_i32 s31, s30, s20
	s_cmp_ge_u32 s30, s20
	s_cselect_b32 s11, s41, s11
	s_cselect_b32 s30, s31, s30
	s_add_i32 s31, s11, 1
	s_cmp_ge_u32 s30, s20
	s_cselect_b32 s11, s31, s11
	s_xor_b32 s11, s11, s21
	s_sub_i32 s11, s11, s21
	s_lshl_b32 s20, s11, 2
	s_sub_i32 s13, s13, s20
	s_min_i32 s13, s13, 4
	s_abs_i32 s21, s13
	s_sub_i32 s30, 0, s21
	s_mul_i32 s11, s11, s12
	s_sub_i32 s10, s10, s11
	s_abs_i32 s11, s10
	s_xor_b32 s12, s10, s13
	s_ashr_i32 s12, s12, 31
	s_mov_b32 s31, 0x40000000
	s_mul_hi_u32 s30, s11, s31
	s_mul_i32 s31, s30, s21
	s_sub_i32 s11, s11, s31
	s_add_i32 s41, s30, 1
	s_sub_i32 s31, s11, s21
	s_cmp_ge_u32 s11, s21
	s_cselect_b32 s30, s41, s30
	s_cselect_b32 s11, s31, s11
	s_add_i32 s31, s30, 1
	s_cmp_ge_u32 s11, s21
	s_cselect_b32 s11, s31, s30
	s_xor_b32 s11, s11, s12
	s_sub_i32 s12, s11, s12
	s_mul_i32 s11, s12, s13
	s_sub_i32 s10, s10, s11
	s_add_i32 s89, s20, s10

;     __device__ __forceinline__ bool next(int i, Unit& u) const {
;     ...
;         const long L = (long)i * G + c; if (L >= nwg) return false;
;         int wgid = (int)L; { const int q = nwg / NXCD, r = nwg % NXCD, xcd = wgid % NXCD, off = wgid / NXCD; wgid = (xcd < r ? xcd * (q + 1) : r * (q + 1) + (xcd - r) * q) + off; }
;         if (rev) wgid = nwg - 1 - wgid;
;         const int per = nM * nN, z = wgid / per, rem = wgid - z * per;
;         const int nig = WGM * nN, gid = rem / nig, fm = gid * WGM, gsz = (nM - fm) < WGM ? (nM - fm) : WGM, ri = rem - gid * nig;
;         u.pm = fm + (ri % gsz); u.pn = ri / gsz; u.z1 = z / Z2; u.z2 = z - u.z1 * Z2; return true;
.LBB0_760:
	s_mov_b32 s9, 8
	s_mov_b32 s10, 1
	s_movk_i32 s8, 0xa0
	s_add_i32 s69, s69, 1
	s_mul_i32 s10, s69, s68
	s_mul_hi_u32 s11, s69, s0
	s_add_i32 s11, s11, s10
	s_mul_i32 s10, s69, s0
	s_add_u32 s10, s10, s2
	s_addc_u32 s11, s11, s33
	s_cmp_lt_u32 s10, 0x500
	s_cselect_b64 s[48:49], exec, 0
	s_cselect_b64 vcc, 0, exec
	s_cbranch_vccnz .LBB0_762
	s_ashr_i32 s11, s10, 31
	s_lshr_b32 s11, s11, 29
	s_add_i32 s11, s10, s11
	s_ashr_i32 s13, s11, 3
	s_and_b32 s11, s11, -8
	s_sub_i32 s10, s10, s11
	s_cmp_lt_i32 s10, 0
	s_movk_i32 s4, 0xa1
	s_mul_i32 s21, s8, s9
	s_cselect_b32 s11, s4, 0xa0
	s_abs_i32 s21, s21
	s_mul_i32 s10, s10, s11
	s_sub_i32 s11, 0, s21
	s_add_i32 s10, s10, s13
	s_ashr_i32 s13, s10, 31
	s_abs_i32 s10, s10
	s_mov_b32 s30, 0x333333
	s_mul_hi_u32 s11, s10, s30
	s_mul_i32 s11, s11, s21
	s_sub_i32 s10, s10, s11
	s_sub_i32 s11, s10, s21
	s_cmp_ge_u32 s10, s21
	s_cselect_b32 s10, s11, s10
	s_sub_i32 s11, s10, s21
	s_cmp_ge_u32 s10, s21
	s_cselect_b32 s10, s11, s10
	s_lshl_b32 s9, s9, 2
	s_abs_i32 s11, s9
	s_xor_b32 s10, s10, s13
	s_sub_i32 s10, s10, s13
	s_sub_i32 s13, 0, s11
	s_abs_i32 s30, s10
	s_xor_b32 s21, s10, s9
	s_ashr_i32 s21, s21, 31
	s_mov_b32 s31, 0x8000000
	s_mul_hi_u32 s13, s30, s31
	s_mul_i32 s31, s13, s11
	s_sub_i32 s30, s30, s31
	s_add_i32 s36, s13, 1
	s_sub_i32 s31, s30, s11
	s_cmp_ge_u32 s30, s11
	s_cselect_b32 s13, s36, s13
	s_cselect_b32 s30, s31, s30
	s_add_i32 s31, s13, 1
	s_cmp_ge_u32 s30, s11
	s_cselect_b32 s11, s31, s13
	s_xor_b32 s11, s11, s21
	s_sub_i32 s11, s11, s21
	s_lshl_b32 s13, s11, 2
	s_sub_i32 s8, s8, s13
	s_min_i32 s8, s8, 4
	s_abs_i32 s21, s8
	s_sub_i32 s30, 0, s21
	s_mul_i32 s11, s11, s9
	s_sub_i32 s9, s10, s11
	s_abs_i32 s10, s9
	s_xor_b32 s11, s9, s8
	s_ashr_i32 s11, s11, 31
	s_mov_b32 s31, 0x40000000
	s_mul_hi_u32 s30, s10, s31
	s_mul_i32 s31, s30, s21
	s_sub_i32 s10, s10, s31
	s_add_i32 s36, s30, 1
	s_sub_i32 s31, s10, s21
	s_cmp_ge_u32 s10, s21
	s_cselect_b32 s30, s36, s30
	s_cselect_b32 s10, s31, s10
	s_add_i32 s31, s30, 1
	s_cmp_ge_u32 s10, s21
	s_cselect_b32 s10, s31, s30
	s_xor_b32 s10, s10, s11
	s_sub_i32 s30, s10, s11
	s_mul_i32 s8, s30, s8
	s_sub_i32 s8, s9, s8
	s_add_i32 s70, s13, s8

;     __device__ __forceinline__ bool next(int i, Unit& u) const {
;     ...
;         const long L = (long)i * G + c; if (L >= nwg) return false;
;         int wgid = (int)L; { const int q = nwg / NXCD, r = nwg % NXCD, xcd = wgid % NXCD, off = wgid / NXCD; wgid = (xcd < r ? xcd * (q + 1) : r * (q + 1) + (xcd - r) * q) + off; }
;         if (rev) wgid = nwg - 1 - wgid;
;         const int per = nM * nN, z = wgid / per, rem = wgid - z * per;
;         const int nig = WGM * nN, gid = rem / nig, fm = gid * WGM, gsz = (nM - fm) < WGM ? (nM - fm) : WGM, ri = rem - gid * nig;
;         u.pm = fm + (ri % gsz); u.pn = ri / gsz; u.z1 = z / Z2; u.z2 = z - u.z1 * Z2; return true;
.LBB0_852:
	s_add_i32 s68, s68, 1
	s_mul_i32 s10, s68, s97
	s_mul_hi_u32 s11, s68, s0
	s_add_i32 s11, s11, s10
	s_mul_i32 s10, s68, s0
	s_add_u32 s10, s10, s2
	s_addc_u32 s11, s11, s33
	s_mov_b32 s9, 8
	s_mov_b32 s8, 1
	s_mov_b32 s13, 4
	s_cmp_lt_u32 s10, 0x280
	s_cselect_b64 s[46:47], exec, 0
	s_cselect_b64 vcc, 0, exec
	s_cbranch_vccnz .LBB0_854
	s_ashr_i32 s11, s10, 31
	s_lshr_b32 s11, s11, 29
	s_add_i32 s11, s10, s11
	s_and_b32 s12, s11, -8
	s_sub_i32 s10, s10, s12
	s_ashr_i32 s11, s11, 3
	s_cmp_lt_i32 s10, 0
	s_mul_i32 s20, s9, s13
	s_cselect_b32 s12, s4, 0xffffffb0
	s_abs_i32 s21, s20
	s_mul_i32 s10, s10, s12
	s_sub_i32 s43, 0, s21
	s_sub_i32 s10, s10, s11
	s_addk_i32 s10, 0x27f
	s_abs_i32 s12, s10
	s_xor_b32 s11, s10, s20
	s_ashr_i32 s11, s11, 31
	s_mov_b32 s44, 0x8000000
	s_mul_hi_u32 s43, s12, s44
	s_mul_i32 s44, s43, s21
	s_sub_i32 s12, s12, s44
	s_add_i32 s44, s43, 1
	s_sub_i32 s45, s12, s21
	s_cmp_ge_u32 s12, s21
	s_cselect_b32 s43, s44, s43
	s_cselect_b32 s12, s45, s12
	s_add_i32 s44, s43, 1
	s_cmp_ge_u32 s12, s21
	s_cselect_b32 s12, s44, s43
	s_lshl_b32 s13, s13, 2
	s_abs_i32 s21, s13
	s_xor_b32 s12, s12, s11
	s_sub_i32 s11, s12, s11
	s_sub_i32 s43, 0, s21
	s_mul_i32 s12, s11, s20
	s_sub_i32 s10, s10, s12
	s_abs_i32 s20, s10
	s_xor_b32 s12, s10, s13
	s_ashr_i32 s12, s12, 31
	s_mov_b32 s44, 0x10000000
	s_mul_hi_u32 s43, s20, s44
	s_mul_i32 s44, s43, s21
	s_sub_i32 s20, s20, s44
	s_add_i32 s44, s43, 1
	s_sub_i32 s45, s20, s21
	s_cmp_ge_u32 s20, s21
	s_cselect_b32 s43, s44, s43
	s_cselect_b32 s20, s45, s20
	s_add_i32 s44, s43, 1
	s_cmp_ge_u32 s20, s21
	s_cselect_b32 s20, s44, s43
	s_xor_b32 s20, s20, s12
	s_sub_i32 s12, s20, s12
	s_lshl_b32 s20, s12, 2
	s_sub_i32 s9, s9, s20
	s_min_i32 s9, s9, 4
	s_abs_i32 s21, s9
	s_sub_i32 s43, 0, s21
	s_mul_i32 s12, s12, s13
	s_sub_i32 s10, s10, s12
	s_abs_i32 s13, s10
	s_xor_b32 s12, s10, s9
	s_ashr_i32 s12, s12, 31
	s_mov_b32 s44, 0x40000000
	s_mul_hi_u32 s43, s13, s44
	s_mul_i32 s44, s43, s21
	s_sub_i32 s13, s13, s44
	s_add_i32 s44, s43, 1
	s_sub_i32 s45, s13, s21
	s_cmp_ge_u32 s13, s21
	s_cselect_b32 s43, s44, s43
	s_cselect_b32 s13, s45, s13
	s_add_i32 s44, s43, 1
	s_cmp_ge_u32 s13, s21
	s_cselect_b32 s13, s44, s43
	s_abs_i32 s21, s8
	s_xor_b32 s13, s13, s12
	s_sub_i32 s12, s13, s12
	s_mul_i32 s9, s12, s9
	s_sub_i32 s9, s10, s9
	s_add_i32 s76, s20, s9
	s_xor_b32 s8, s11, s8
	s_abs_i32 s9, s11
	s_sub_i32 s10, 0, s21
	s_ashr_i32 s8, s8, 31
	s_mov_b32 s11, 0xffffffff
	s_mul_hi_u32 s10, s9, s11
	s_mul_i32 s11, s10, s21
	s_sub_i32 s9, s9, s11
	s_add_i32 s11, s10, 1
	s_sub_i32 s13, s9, s21
	s_cmp_ge_u32 s9, s21
	s_cselect_b32 s10, s11, s10
	s_cselect_b32 s9, s13, s9
	s_add_i32 s11, s10, 1
	s_cmp_ge_u32 s9, s21
	s_cselect_b32 s9, s11, s10
	s_xor_b32 s9, s9, s8
	s_sub_i32 s60, s9, s8

;     __device__ __forceinline__ bool next(int i, Unit& u) const {
;     ...
;         const long L = (long)i * G + c; if (L >= nwg) return false;
;         int wgid = (int)L; { const int q = nwg / NXCD, r = nwg % NXCD, xcd = wgid % NXCD, off = wgid / NXCD; wgid = (xcd < r ? xcd * (q + 1) : r * (q + 1) + (xcd - r) * q) + off; }
;         if (rev) wgid = nwg - 1 - wgid;
;         const int per = nM * nN, z = wgid / per, rem = wgid - z * per;
;         const int nig = WGM * nN, gid = rem / nig, fm = gid * WGM, gsz = (nM - fm) < WGM ? (nM - fm) : WGM, ri = rem - gid * nig;
;         u.pm = fm + (ri % gsz); u.pn = ri / gsz; u.z1 = z / Z2; u.z2 = z - u.z1 * Z2; return true;
.LBB0_952:
	s_add_i32 s90, s90, 1
	s_mul_i32 s10, s90, s89
	s_mul_hi_u32 s11, s90, s0
	s_add_i32 s11, s11, s10
	s_mul_i32 s10, s90, s0
	s_add_u32 s10, s10, s2
	s_addc_u32 s11, s11, s33
	s_mov_b32 s9, 8
	s_mov_b32 s13, 8
	s_mov_b32 s8, 1
	s_cmp_lt_u32 s10, 0x500
	s_cselect_b64 s[46:47], exec, 0
	s_cselect_b64 vcc, 0, exec
	s_cbranch_vccnz .LBB0_954
	s_ashr_i32 s11, s10, 31
	s_lshr_b32 s11, s11, 29
	s_add_i32 s11, s10, s11
	s_ashr_i32 s21, s11, 3
	s_and_b32 s11, s11, -8
	s_sub_i32 s10, s10, s11
	s_cmp_lt_i32 s10, 0
	s_movk_i32 s4, 0xa1
	s_mul_i32 s31, s9, s13
	s_cselect_b32 s11, s4, 0xa0
	s_abs_i32 s36, s31
	s_mul_i32 s10, s10, s11
	s_sub_i32 s11, 0, s36
	s_add_i32 s10, s10, s21
	s_abs_i32 s37, s10
	s_xor_b32 s21, s10, s31
	s_ashr_i32 s21, s21, 31
	s_mov_b32 s42, 0x4000000
	s_mul_hi_u32 s11, s37, s42
	s_mul_i32 s42, s11, s36
	s_sub_i32 s37, s37, s42
	s_add_i32 s42, s11, 1
	s_sub_i32 s43, s37, s36
	s_cmp_ge_u32 s37, s36
	s_cselect_b32 s11, s42, s11
	s_cselect_b32 s37, s43, s37
	s_add_i32 s42, s11, 1
	s_cmp_ge_u32 s37, s36
	s_cselect_b32 s11, s42, s11
	s_lshl_b32 s13, s13, 2
	s_abs_i32 s36, s13
	s_xor_b32 s11, s11, s21
	s_sub_i32 s11, s11, s21
	s_sub_i32 s37, 0, s36
	s_mul_i32 s21, s11, s31
	s_sub_i32 s10, s10, s21
	s_abs_i32 s31, s10
	s_xor_b32 s21, s10, s13
	s_ashr_i32 s21, s21, 31
	s_mov_b32 s42, 0x8000000
	s_mul_hi_u32 s37, s31, s42
	s_mul_i32 s42, s37, s36
	s_sub_i32 s31, s31, s42
	s_add_i32 s42, s37, 1
	s_sub_i32 s43, s31, s36
	s_cmp_ge_u32 s31, s36
	s_cselect_b32 s37, s42, s37
	s_cselect_b32 s31, s43, s31
	s_add_i32 s42, s37, 1
	s_cmp_ge_u32 s31, s36
	s_cselect_b32 s31, s42, s37
	s_xor_b32 s31, s31, s21
	s_sub_i32 s21, s31, s21
	s_lshl_b32 s31, s21, 2
	s_sub_i32 s9, s9, s31
	s_min_i32 s9, s9, 4
	s_abs_i32 s36, s9
	s_sub_i32 s37, 0, s36
	s_mul_i32 s21, s21, s13
	s_sub_i32 s10, s10, s21
	s_abs_i32 s21, s10
	s_xor_b32 s13, s10, s9
	s_ashr_i32 s13, s13, 31
	s_mov_b32 s42, 0x40000000
	s_mul_hi_u32 s37, s21, s42
	s_mul_i32 s42, s37, s36
	s_sub_i32 s21, s21, s42
	s_add_i32 s42, s37, 1
	s_sub_i32 s43, s21, s36
	s_cmp_ge_u32 s21, s36
	s_cselect_b32 s37, s42, s37
	s_cselect_b32 s21, s43, s21
	s_add_i32 s42, s37, 1
	s_cmp_ge_u32 s21, s36
	s_cselect_b32 s21, s42, s37
	s_abs_i32 s37, s8
	s_xor_b32 s21, s21, s13
	s_sub_i32 s36, s21, s13
	s_mul_i32 s9, s36, s9
	s_sub_i32 s9, s10, s9
	s_add_i32 s42, s31, s9
	s_xor_b32 s8, s11, s8
	s_abs_i32 s9, s11
	s_sub_i32 s10, 0, s37
	s_ashr_i32 s8, s8, 31
	s_mov_b32 s11, 0xffffffff
	s_mul_hi_u32 s10, s9, s11
	s_mul_i32 s11, s10, s37
	s_sub_i32 s9, s9, s11
	s_add_i32 s11, s10, 1
	s_sub_i32 s13, s9, s37
	s_cmp_ge_u32 s9, s37
	s_cselect_b32 s10, s11, s10
	s_cselect_b32 s9, s13, s9
	s_add_i32 s11, s10, 1
	s_cmp_ge_u32 s9, s37
	s_cselect_b32 s9, s11, s10
	s_xor_b32 s9, s9, s8
	s_sub_i32 s48, s9, s8

;     __device__ __forceinline__ bool next(int i, Unit& u) const {
;     ...
;         const long L = (long)i * G + c; if (L >= nwg) return false;
;         int wgid = (int)L; { const int q = nwg / NXCD, r = nwg % NXCD, xcd = wgid % NXCD, off = wgid / NXCD; wgid = (xcd < r ? xcd * (q + 1) : r * (q + 1) + (xcd - r) * q) + off; }
;         if (rev) wgid = nwg - 1 - wgid;
;         const int per = nM * nN, z = wgid / per, rem = wgid - z * per;
;         const int nig = WGM * nN, gid = rem / nig, fm = gid * WGM, gsz = (nM - fm) < WGM ? (nM - fm) : WGM, ri = rem - gid * nig;
;         u.pm = fm + (ri % gsz); u.pn = ri / gsz; u.z1 = z / Z2; u.z2 = z - u.z1 * Z2; return true;
.LBB0_1103:
	s_mov_b32 s10, 1
	s_mov_b32 s9, 44
	s_movk_i32 s8, 0xa0
	s_add_i32 s67, s67, 1
	s_mul_i32 s10, s67, s66
	s_mul_hi_u32 s11, s67, s68
	s_add_i32 s11, s11, s10
	s_mul_i32 s10, s67, s68
	s_add_u32 s10, s10, s2
	s_addc_u32 s11, s11, s33
	s_cmp_lt_u32 s10, 0x1b80
	s_cselect_b64 s[46:47], exec, 0
	s_cselect_b64 vcc, 0, exec
	s_cbranch_vccnz .LBB0_1105
	s_ashr_i32 s11, s10, 31
	s_lshr_b32 s11, s11, 29
	s_add_i32 s11, s10, s11
	s_and_b32 s48, s11, -8
	s_sub_i32 s10, s10, s48
	s_ashr_i32 s11, s11, 3
	s_cmp_lt_i32 s10, 0
	s_movk_i32 s4, 0xfc8f
	s_mul_i32 s49, s8, s9
	s_cselect_b32 s48, s4, 0xfffffc90
	s_abs_i32 s49, s49
	s_mul_i32 s10, s10, s48
	s_sub_i32 s48, 0, s49
	s_sub_i32 s10, s10, s11
	s_addk_i32 s10, 0x1b7f
	s_ashr_i32 s11, s10, 31
	s_abs_i32 s10, s10
	s_mov_b32 s50, 0x94f20
	s_mul_hi_u32 s48, s10, s50
	s_mul_i32 s48, s48, s49
	s_sub_i32 s10, s10, s48
	s_sub_i32 s48, s10, s49
	s_cmp_ge_u32 s10, s49
	s_cselect_b32 s10, s48, s10
	s_sub_i32 s48, s10, s49
	s_cmp_ge_u32 s10, s49
	s_cselect_b32 s10, s48, s10
	s_lshl_b32 s9, s9, 2
	s_abs_i32 s48, s9
	s_xor_b32 s10, s10, s11
	s_sub_i32 s10, s10, s11
	s_sub_i32 s11, 0, s48
	s_abs_i32 s50, s10
	s_xor_b32 s49, s10, s9
	s_ashr_i32 s49, s49, 31
	s_mov_b32 s51, 0x1745d17
	s_mul_hi_u32 s11, s50, s51
	s_mul_i32 s51, s11, s48
	s_sub_i32 s50, s50, s51
	s_add_i32 s54, s11, 1
	s_sub_i32 s51, s50, s48
	s_cmp_ge_u32 s50, s48
	s_cselect_b32 s11, s54, s11
	s_cselect_b32 s50, s51, s50
	s_add_i32 s51, s11, 1
	s_cmp_ge_u32 s50, s48
	s_cselect_b32 s11, s51, s11
	s_xor_b32 s11, s11, s49
	s_sub_i32 s11, s11, s49
	s_lshl_b32 s49, s11, 2
	s_sub_i32 s8, s8, s49
	s_min_i32 s8, s8, 4
	s_abs_i32 s48, s8
	s_sub_i32 s50, 0, s48
	s_mul_i32 s11, s11, s9
	s_sub_i32 s9, s10, s11
	s_abs_i32 s10, s9
	s_xor_b32 s11, s9, s8
	s_ashr_i32 s11, s11, 31
	s_mov_b32 s51, 0x40000000
	s_mul_hi_u32 s50, s10, s51
	s_mul_i32 s51, s50, s48
	s_sub_i32 s10, s10, s51
	s_add_i32 s54, s50, 1
	s_sub_i32 s51, s10, s48
	s_cmp_ge_u32 s10, s48
	s_cselect_b32 s50, s54, s50
	s_cselect_b32 s10, s51, s10
	s_add_i32 s51, s50, 1
	s_cmp_ge_u32 s10, s48
	s_cselect_b32 s10, s51, s50
	s_xor_b32 s10, s10, s11
	s_sub_i32 s48, s10, s11
	s_mul_i32 s8, s48, s8
	s_sub_i32 s8, s9, s8
	s_add_i32 s50, s49, s8

;     __device__ __forceinline__ bool next(int i, Unit& u) const {
;     ...
;         const long L = (long)i * G + c; if (L >= nwg) return false;
;         int wgid = (int)L; { const int q = nwg / NXCD, r = nwg % NXCD, xcd = wgid % NXCD, off = wgid / NXCD; wgid = (xcd < r ? xcd * (q + 1) : r * (q + 1) + (xcd - r) * q) + off; }
;         if (rev) wgid = nwg - 1 - wgid;
;         const int per = nM * nN, z = wgid / per, rem = wgid - z * per;
;         const int nig = WGM * nN, gid = rem / nig, fm = gid * WGM, gsz = (nM - fm) < WGM ? (nM - fm) : WGM, ri = rem - gid * nig;
;         u.pm = fm + (ri % gsz); u.pn = ri / gsz; u.z1 = z / Z2; u.z2 = z - u.z1 * Z2; return true;
.LBB0_1297:
	s_mov_b32 s8, 8
	s_mov_b32 s4, 1
	s_movk_i32 s1, 0xa0
	s_add_i32 s67, s67, 1
	s_mul_i32 s4, s67, s66
	s_mul_hi_u32 s5, s67, s46
	s_add_i32 s5, s5, s4
	s_mul_i32 s4, s67, s46
	s_add_u32 s10, s4, s2
	s_addc_u32 s11, s5, s33
	s_cmp_lt_u32 s10, 0x500
	s_cselect_b64 s[44:45], exec, 0
	s_cselect_b64 vcc, 0, exec
	s_cbranch_vccnz .LBB0_1299
	s_ashr_i32 s4, s10, 31
	s_lshr_b32 s4, s4, 29
	s_add_i32 s4, s10, s4
	s_ashr_i32 s5, s4, 3
	s_and_b32 s4, s4, -8
	s_sub_i32 s4, s10, s4
	s_cmp_lt_i32 s4, 0
	s_movk_i32 s9, 0xa1
	s_mul_i32 s10, s1, s8
	s_cselect_b32 s9, s9, 0xa0
	s_abs_i32 s10, s10
	s_mul_i32 s4, s4, s9
	s_sub_i32 s9, 0, s10
	s_add_i32 s4, s4, s5
	s_ashr_i32 s5, s4, 31
	s_abs_i32 s4, s4
	s_mov_b32 s11, 0x333333
	s_mul_hi_u32 s9, s4, s11
	s_mul_i32 s9, s9, s10
	s_sub_i32 s4, s4, s9
	s_sub_i32 s9, s4, s10
	s_cmp_ge_u32 s4, s10
	s_cselect_b32 s4, s9, s4
	s_sub_i32 s9, s4, s10
	s_cmp_ge_u32 s4, s10
	s_cselect_b32 s4, s9, s4
	s_lshl_b32 s8, s8, 2
	s_abs_i32 s9, s8
	s_xor_b32 s4, s4, s5
	s_sub_i32 s4, s4, s5
	s_sub_i32 s5, 0, s9
	s_abs_i32 s11, s4
	s_xor_b32 s10, s4, s8
	s_ashr_i32 s10, s10, 31
	s_mov_b32 s13, 0x8000000
	s_mul_hi_u32 s5, s11, s13
	s_mul_i32 s13, s5, s9
	s_sub_i32 s11, s11, s13
	s_add_i32 s20, s5, 1
	s_sub_i32 s13, s11, s9
	s_cmp_ge_u32 s11, s9
	s_cselect_b32 s5, s20, s5
	s_cselect_b32 s11, s13, s11
	s_add_i32 s13, s5, 1
	s_cmp_ge_u32 s11, s9
	s_cselect_b32 s5, s13, s5
	s_xor_b32 s5, s5, s10
	s_sub_i32 s5, s5, s10
	s_lshl_b32 s9, s5, 2
	s_sub_i32 s1, s1, s9
	s_min_i32 s1, s1, 4
	s_abs_i32 s10, s1
	s_sub_i32 s11, 0, s10
	s_mul_i32 s5, s5, s8
	s_sub_i32 s4, s4, s5
	s_abs_i32 s5, s4
	s_xor_b32 s8, s4, s1
	s_ashr_i32 s8, s8, 31
	s_mov_b32 s13, 0x40000000
	s_mul_hi_u32 s11, s5, s13
	s_mul_i32 s13, s11, s10
	s_sub_i32 s5, s5, s13
	s_add_i32 s20, s11, 1
	s_sub_i32 s13, s5, s10
	s_cmp_ge_u32 s5, s10
	s_cselect_b32 s11, s20, s11
	s_cselect_b32 s5, s13, s5
	s_add_i32 s13, s11, 1
	s_cmp_ge_u32 s5, s10
	s_cselect_b32 s5, s13, s11
	s_xor_b32 s5, s5, s8
	s_sub_i32 s68, s5, s8
	s_mul_i32 s1, s68, s1
	s_sub_i32 s1, s4, s1
	s_add_i32 s69, s9, s1
